# differential attention stage loop: K1|K2|V^T staged with global_load_lds_dwordx4 straight into the idle LDS buffer (linear image) instead of 32 VGPRs + 8 ds_write_b128 per thread (on v93)
# speedup vs baseline: 1.0056x; 1.0024x over previous
.LBB0_303:
	s_cmp_lg_u32 s88, -1
	s_cselect_b64 s[46:47], -1, 0
	s_cmp_eq_u32 s88, -1
	s_cbranch_scc1 .LBB0_305
	s_lshl_b64 s[8:9], s[88:89], 20
	v_lshl_add_u64 v[2:3], v[192:193], 0, s[8:9]
	v_add_co_u32_e32 v4, vcc, 0x80000, v2
	s_lshl_b64 s[8:9], s[88:89], 8
	s_nop 0
	v_addc_co_u32_e32 v5, vcc, 0, v3, vcc
	v_readfirstlane_b32 s98, v164
	s_lshr_b32 s98, s98, 6
	s_lshl_b32 s98, s98, 10
	s_and_b32 s99, s57, 0x10000
	s_xor_b32 s99, s99, 0x10000
	s_add_i32 s98, s98, s99
	s_mov_b64 s[100:101], 0x80
	v_lshl_add_u64 v[132:133], v[2:3], 0, s[100:101]
	v_lshl_add_u64 v[134:135], v[4:5], 0, s[100:101]
	s_add_i32 m0, s98, 0x0
	s_nop 0
	global_load_lds_dwordx4 v[2:3], off
	s_add_i32 m0, s98, 0x4000
	s_nop 0
	global_load_lds_dwordx4 v[132:133], off
	s_add_i32 m0, s98, 0x2000
	s_nop 0
	global_load_lds_dwordx4 v[4:5], off
	s_add_i32 m0, s98, 0x6000
	s_nop 0
	global_load_lds_dwordx4 v[134:135], off
	v_lshl_add_u64 v[2:3], v[190:191], 0, s[8:9]
	v_lshl_add_u64 v[4:5], v[194:195], 0, s[8:9]
	s_add_i32 m0, s98, 0x8000
	s_nop 0
	global_load_lds_dwordx4 v[2:3], off
	s_add_i32 m0, s98, 0xa000
	s_nop 0
	global_load_lds_dwordx4 v[4:5], off
	v_lshl_add_u64 v[2:3], v[196:197], 0, s[8:9]
	v_lshl_add_u64 v[4:5], v[198:199], 0, s[8:9]
	s_add_i32 m0, s98, 0xc000
	s_nop 0
	global_load_lds_dwordx4 v[2:3], off
	s_add_i32 m0, s98, 0xe000
	s_nop 0
	global_load_lds_dwordx4 v[4:5], off

.LBB0_310:
	s_xor_b32 s8, s62, 0x10000
	v_add_u32_e32 v1, s8, v204
	s_add_i32 s8, s58, -1
	v_cvt_f32_u32_e32 v2, s8
	s_waitcnt vmcnt(0)
	v_fma_f32 v1, -v214, v2, v215
	v_sub_f32_e32 v1, v1, v246
	v_cmp_gt_f32_e32 vcc, s53, v1
	s_cmp_eq_u64 vcc, exec
	s_cselect_b64 s[8:9], -1, 0
	s_branch .LBB0_404
